# v-pass expert-range rounds: 4 rounds of 4096 experts instead of 8 rounds of 2048 (fuller gather batches)
# baseline (speedup 1.0000x reference)
; #define AS1 __attribute__((address_space(1)))
; DI void peer_v_group(const Params& p, int gw, int nw, int g, const float* wlw  ) {
;     ...
; #pragma unroll
;   for (int ts = 0; ts < 4; ++ts) {
;     const int k = g * 4 + ts;
;     const int row = gw + k * nw;
;     valid[ts] = row < MT;
; #pragma unroll
;     for (int i = 0; i < 16; ++i) out[ts][i] = 0.f;
;     e0[ts] = 0x7fffffff; e1[ts] = 0x7fffffff; w0[ts] = 0.f; w1[ts] = 0.f;
;     if (valid[ts]) {
;       e0[ts] = ((const int AS1*)p.eid)[(size_t)row * 128 + lane];
;       e1[ts] = ((const int AS1*)p.eid)[(size_t)row * 128 + 64 + lane];
;       w0[ts] = wlw[k * 128 + lane];
;       w1[ts] = wlw[k * 128 + 64 + lane];
;     }
;   }
; #pragma unroll 1
;   for (int r = 0; r < 8; ++r) {
; #pragma unroll
;     for (int ts = 0; ts < 4; ++ts) {
;       unsigned long long m0 = __ballot((e0[ts] >> 11) == r);
;       unsigned long long m1 = __ballot((e1[ts] >> 11) == r);
.LBB0_1366:
	s_or_b64 exec, exec, s[6:7]
	v_mov_b32_e32 v36, v37
	s_waitcnt vmcnt(0)
	v_ashrrev_i32_e32 v140, 12, v135
	v_ashrrev_i32_e32 v141, 12, v136
	v_ashrrev_i32_e32 v142, 12, v69
	v_ashrrev_i32_e32 v143, 12, v137
	v_ashrrev_i32_e32 v144, 12, v51
	v_ashrrev_i32_e32 v145, 12, v138
	v_ashrrev_i32_e32 v146, 12, v49
	v_ashrrev_i32_e32 v147, 12, v139
	s_mov_b32 s37, 0
	v_mov_b64_e32 v[52:53], v[36:37]
	v_mov_b64_e32 v[54:55], v[36:37]
	v_mov_b64_e32 v[56:57], v[36:37]
	v_mov_b64_e32 v[58:59], v[36:37]
	v_mov_b64_e32 v[60:61], v[36:37]
	v_mov_b64_e32 v[62:63], v[36:37]
	v_mov_b64_e32 v[64:65], v[36:37]
	v_mov_b64_e32 v[66:67], v[36:37]
	v_mov_b64_e32 v[70:71], v[36:37]
	v_mov_b64_e32 v[72:73], v[36:37]
	v_mov_b64_e32 v[74:75], v[36:37]
	v_mov_b64_e32 v[76:77], v[36:37]
	v_mov_b64_e32 v[78:79], v[36:37]
	v_mov_b64_e32 v[80:81], v[36:37]
	v_mov_b64_e32 v[82:83], v[36:37]
	v_mov_b64_e32 v[84:85], v[36:37]
	v_mov_b64_e32 v[88:89], v[36:37]
	v_mov_b64_e32 v[90:91], v[36:37]
	v_mov_b64_e32 v[92:93], v[36:37]
	v_mov_b64_e32 v[94:95], v[36:37]
	v_mov_b64_e32 v[96:97], v[36:37]
	v_mov_b64_e32 v[98:99], v[36:37]
	v_mov_b64_e32 v[100:101], v[36:37]
	v_mov_b64_e32 v[102:103], v[36:37]
	v_mov_b64_e32 v[112:113], v[36:37]
	v_mov_b64_e32 v[114:115], v[36:37]
	v_mov_b64_e32 v[116:117], v[36:37]
	v_mov_b64_e32 v[118:119], v[36:37]
	v_mov_b64_e32 v[120:121], v[36:37]
	v_mov_b64_e32 v[122:123], v[36:37]
	v_mov_b64_e32 v[124:125], v[36:37]
	v_mov_b64_e32 v[126:127], v[36:37]
	s_branch .LBB0_1368
.LBB0_1367:
	s_add_i32 s37, s37, 1
	s_cmp_eq_u32 s37, 4
	s_cbranch_scc1 .LBB0_1572
